# v82 + phase 4: workgroups without a GLU tile start conv when their panel's GLU tiles have counted in (one-lane poll + barrier)
# baseline (speedup 1.0000x reference)
.LBB0_589:
	s_cmp_gt_i32 s26, 4
	s_cselect_b64 s[4:5], -1, 0
	s_xor_b64 s[0:1], s[0:1], -1
	s_or_b64 s[0:1], s[4:5], s[0:1]
	s_and_b64 vcc, exec, s[0:1]
	s_cbranch_vccnz .LBB0_771
	s_cmpk_lt_u32 s96, 0x80
	s_cbranch_scc1 .Lp4_go
	s_and_b32 s98, s96, 7
	s_lshl_b32 s98, s98, 3
	s_bfe_u32 s99, s96, 0x30003
	s_or_b32 s98, s98, s99
	s_lshl_b32 s98, s98, 8
	s_add_u32 s98, s78, s98
	s_addc_u32 s99, s79, 0
	s_add_u32 s98, s98, 0xe81e000
	s_addc_u32 s99, s99, 0
	v_and_b32_e32 v2, 0x3ff, v0
	v_cmp_eq_u32_e32 vcc, 0, v2
	s_and_saveexec_b64 s[100:101], vcc
	s_cbranch_execz .Lp4_polled
	v_mov_b32_e32 v2, 0
	v_mov_b32_e32 v4, 0x2000
.Lp4_wait:
	global_load_dword v3, v2, s[98:99] sc1
	s_waitcnt vmcnt(0)
	v_cmp_lt_u32_e32 vcc, 1, v3
	s_cbranch_vccnz .Lp4_polled
	s_sleep 2
	v_add_u32_e32 v4, -1, v4
	v_cmp_ne_u32_e32 vcc, 0, v4
	s_cbranch_vccnz .Lp4_wait
.Lp4_polled:
	s_or_b64 exec, exec, s[100:101]
	s_barrier
